# conv_win weight transposes: all loads of an item batched before one wait (P0 fast path + layer-1 variant), was 16-32 serialized round trips per item
# speedup vs baseline: 1.0230x; 1.0194x over previous
.LBB0_51:
	v_mov_b32_e32 v21, v217
	s_lshl_b32 s12, s5, 6
	s_ashr_i32 s5, s4, 31
	v_ashrrev_i32_e32 v2, 5, v21
	s_ashr_i32 s13, s12, 31
	v_ashrrev_i32_e32 v3, 31, v2
	s_lshl_b64 s[4:5], s[4:5], 2
	s_load_dwordx16 s[36:51], s[0:1], 0x0
	v_lshl_add_u64 v[10:11], v[2:3], 0, s[12:13]
	v_lshlrev_b32_e32 v0, 2, v21
	v_add_u32_e32 v23, s12, v2
	v_mov_b64_e32 v[18:19], s[4:5]
	v_mul_lo_u32 v3, v2, s16
	v_and_b32_e32 v0, 0x7c, v0
	v_add_u32_e32 v2, 14, v23
	v_add_u32_e32 v4, 12, v23
	v_mad_u64_u32 v[6:7], s[4:5], v10, s17, v[18:19]
	v_add_u32_e32 v8, 10, v23
	v_add_u32_e32 v12, 8, v23
	v_add_u32_e32 v14, 6, v23
	v_add_u32_e32 v16, 4, v23
	v_add_u32_e32 v23, 2, v23
	v_add3_u32 v22, v3, v0, s70
	v_mad_i64_i32 v[2:3], s[4:5], v2, s17, v[18:19]
	v_mad_i64_i32 v[4:5], s[4:5], v4, s17, v[18:19]
	v_mad_i32_i24 v7, v11, s17, v7
	v_mad_i64_i32 v[8:9], s[4:5], v8, s17, v[18:19]
	v_mad_i64_i32 v[12:13], s[4:5], v12, s17, v[18:19]
	v_mad_i64_i32 v[14:15], s[4:5], v14, s17, v[18:19]
	v_mad_i64_i32 v[16:17], s[4:5], v16, s17, v[18:19]
	v_mad_i64_i32 v[18:19], s[4:5], v23, s17, v[18:19]
	v_lshl_add_u64 v[2:3], v[2:3], 0, v[0:1]
	v_lshl_add_u64 v[4:5], v[4:5], 0, v[0:1]
	v_lshl_add_u64 v[6:7], v[6:7], 0, v[0:1]
	v_lshl_add_u64 v[8:9], v[8:9], 0, v[0:1]
	v_lshl_add_u64 v[12:13], v[12:13], 0, v[0:1]
	v_lshl_add_u64 v[14:15], v[14:15], 0, v[0:1]
	v_lshl_add_u64 v[16:17], v[16:17], 0, v[0:1]
	v_lshl_add_u64 v[18:19], v[18:19], 0, v[0:1]
	s_waitcnt lgkmcnt(0)
	v_lshl_add_u64 v[2:3], s[40:41], 0, v[2:3]
	v_lshl_add_u64 v[4:5], s[40:41], 0, v[4:5]
	v_lshl_add_u64 v[6:7], s[40:41], 0, v[6:7]
	v_lshl_add_u64 v[8:9], s[40:41], 0, v[8:9]
	v_lshl_add_u64 v[10:11], v[10:11], 2, s[10:11]
	v_lshl_add_u64 v[12:13], s[40:41], 0, v[12:13]
	v_lshl_add_u64 v[14:15], s[40:41], 0, v[14:15]
	v_lshl_add_u64 v[16:17], s[40:41], 0, v[16:17]
	v_lshl_add_u64 v[18:19], s[40:41], 0, v[18:19]
	s_mov_b64 s[14:15], 0
	s_and_b64 vcc, exec, s[8:9]
	s_cbranch_vccnz .Lcw0_fast
	s_branch .LBB0_53

.Lcw0_fast:
	global_load_dword v96, v[10:11], off offset:-32
	global_load_dword v97, v[10:11], off offset:-24
	global_load_dword v98, v[10:11], off offset:-16
	global_load_dword v99, v[10:11], off offset:-8
	global_load_dword v100, v[10:11], off
	global_load_dword v101, v[10:11], off offset:8
	global_load_dword v102, v[10:11], off offset:16
	global_load_dword v103, v[10:11], off offset:24
	global_load_dword v104, v[10:11], off offset:32
	global_load_dword v105, v[10:11], off offset:40
	global_load_dword v106, v[10:11], off offset:48
	global_load_dword v107, v[10:11], off offset:56
	global_load_dword v108, v[10:11], off offset:64
	global_load_dword v109, v[10:11], off offset:72
	global_load_dword v110, v[10:11], off offset:80
	global_load_dword v111, v[10:11], off offset:88
	global_load_dword v112, v[10:11], off offset:96
	global_load_dword v113, v[10:11], off offset:104
	global_load_dword v114, v[10:11], off offset:112
	global_load_dword v115, v[10:11], off offset:120
	global_load_dword v116, v[10:11], off offset:128
	global_load_dword v117, v[10:11], off offset:136
	global_load_dword v118, v[10:11], off offset:144
	global_load_dword v119, v[10:11], off offset:152
	global_load_dword v120, v[10:11], off offset:160
	global_load_dword v121, v[10:11], off offset:168
	global_load_dword v122, v[10:11], off offset:176
	global_load_dword v123, v[10:11], off offset:184
	global_load_dword v124, v[10:11], off offset:192
	global_load_dword v125, v[10:11], off offset:200
	global_load_dword v126, v[10:11], off offset:208
	global_load_dword v127, v[10:11], off offset:216
	v_lshl_add_u64 v[24:25], v[6:7], 0, s[14:15]
	global_load_dword v64, v[24:25], off
	v_lshl_add_u64 v[24:25], v[18:19], 0, s[14:15]
	global_load_dword v65, v[24:25], off
	v_lshl_add_u64 v[24:25], v[16:17], 0, s[14:15]
	global_load_dword v66, v[24:25], off
	v_lshl_add_u64 v[24:25], v[14:15], 0, s[14:15]
	global_load_dword v67, v[24:25], off
	v_lshl_add_u64 v[24:25], v[12:13], 0, s[14:15]
	global_load_dword v68, v[24:25], off
	v_lshl_add_u64 v[24:25], v[8:9], 0, s[14:15]
	global_load_dword v69, v[24:25], off
	v_lshl_add_u64 v[24:25], v[4:5], 0, s[14:15]
	global_load_dword v70, v[24:25], off
	v_lshl_add_u64 v[24:25], v[2:3], 0, s[14:15]
	global_load_dword v71, v[24:25], off
	s_add_u32 s14, s14, 0x68000
	s_addc_u32 s15, s15, 0
	v_lshl_add_u64 v[24:25], v[6:7], 0, s[14:15]
	global_load_dword v72, v[24:25], off
	v_lshl_add_u64 v[24:25], v[18:19], 0, s[14:15]
	global_load_dword v73, v[24:25], off
	v_lshl_add_u64 v[24:25], v[16:17], 0, s[14:15]
	global_load_dword v74, v[24:25], off
	v_lshl_add_u64 v[24:25], v[14:15], 0, s[14:15]
	global_load_dword v75, v[24:25], off
	v_lshl_add_u64 v[24:25], v[12:13], 0, s[14:15]
	global_load_dword v76, v[24:25], off
	v_lshl_add_u64 v[24:25], v[8:9], 0, s[14:15]
	global_load_dword v77, v[24:25], off
	v_lshl_add_u64 v[24:25], v[4:5], 0, s[14:15]
	global_load_dword v78, v[24:25], off
	v_lshl_add_u64 v[24:25], v[2:3], 0, s[14:15]
	global_load_dword v79, v[24:25], off
	s_add_u32 s14, s14, 0x68000
	s_addc_u32 s15, s15, 0
	v_lshl_add_u64 v[24:25], v[6:7], 0, s[14:15]
	global_load_dword v80, v[24:25], off
	v_lshl_add_u64 v[24:25], v[18:19], 0, s[14:15]
	global_load_dword v81, v[24:25], off
	v_lshl_add_u64 v[24:25], v[16:17], 0, s[14:15]
	global_load_dword v82, v[24:25], off
	v_lshl_add_u64 v[24:25], v[14:15], 0, s[14:15]
	global_load_dword v83, v[24:25], off
	v_lshl_add_u64 v[24:25], v[12:13], 0, s[14:15]
	global_load_dword v84, v[24:25], off
	v_lshl_add_u64 v[24:25], v[8:9], 0, s[14:15]
	global_load_dword v85, v[24:25], off
	v_lshl_add_u64 v[24:25], v[4:5], 0, s[14:15]
	global_load_dword v86, v[24:25], off
	v_lshl_add_u64 v[24:25], v[2:3], 0, s[14:15]
	global_load_dword v87, v[24:25], off
	s_add_u32 s14, s14, 0x68000
	s_addc_u32 s15, s15, 0
	s_waitcnt vmcnt(23)
	v_mul_f32_e32 v64, v64, v96
	ds_write_b32 v22, v64
	s_waitcnt vmcnt(22)
	v_mul_f32_e32 v65, v65, v97
	ds_write_b32 v22, v65 offset:264
	s_waitcnt vmcnt(21)
	v_mul_f32_e32 v66, v66, v98
	ds_write_b32 v22, v66 offset:528
	s_waitcnt vmcnt(20)
	v_mul_f32_e32 v67, v67, v99
	ds_write_b32 v22, v67 offset:792
	s_waitcnt vmcnt(19)
	v_mul_f32_e32 v68, v68, v100
	ds_write_b32 v22, v68 offset:1056
	s_waitcnt vmcnt(18)
	v_mul_f32_e32 v69, v69, v101
	ds_write_b32 v22, v69 offset:1320
	s_waitcnt vmcnt(17)
	v_mul_f32_e32 v70, v70, v102
	ds_write_b32 v22, v70 offset:1584
	s_waitcnt vmcnt(16)
	v_mul_f32_e32 v71, v71, v103
	ds_write_b32 v22, v71 offset:1848
	v_lshl_add_u64 v[24:25], v[6:7], 0, s[14:15]
	global_load_dword v88, v[24:25], off
	v_lshl_add_u64 v[24:25], v[18:19], 0, s[14:15]
	global_load_dword v89, v[24:25], off
	v_lshl_add_u64 v[24:25], v[16:17], 0, s[14:15]
	global_load_dword v90, v[24:25], off
	v_lshl_add_u64 v[24:25], v[14:15], 0, s[14:15]
	global_load_dword v91, v[24:25], off
	v_lshl_add_u64 v[24:25], v[12:13], 0, s[14:15]
	global_load_dword v92, v[24:25], off
	v_lshl_add_u64 v[24:25], v[8:9], 0, s[14:15]
	global_load_dword v93, v[24:25], off
	v_lshl_add_u64 v[24:25], v[4:5], 0, s[14:15]
	global_load_dword v94, v[24:25], off
	v_lshl_add_u64 v[24:25], v[2:3], 0, s[14:15]
	global_load_dword v95, v[24:25], off
	s_waitcnt vmcnt(23)
	v_mul_f32_e32 v72, v72, v104
	ds_write_b32 v22, v72 offset:2112
	s_waitcnt vmcnt(22)
	v_mul_f32_e32 v73, v73, v105
	ds_write_b32 v22, v73 offset:2376
	s_waitcnt vmcnt(21)
	v_mul_f32_e32 v74, v74, v106
	ds_write_b32 v22, v74 offset:2640
	s_waitcnt vmcnt(20)
	v_mul_f32_e32 v75, v75, v107
	ds_write_b32 v22, v75 offset:2904
	s_waitcnt vmcnt(19)
	v_mul_f32_e32 v76, v76, v108
	ds_write_b32 v22, v76 offset:3168
	s_waitcnt vmcnt(18)
	v_mul_f32_e32 v77, v77, v109
	ds_write_b32 v22, v77 offset:3432
	s_waitcnt vmcnt(17)
	v_mul_f32_e32 v78, v78, v110
	ds_write_b32 v22, v78 offset:3696
	s_waitcnt vmcnt(16)
	v_mul_f32_e32 v79, v79, v111
	ds_write_b32 v22, v79 offset:3960
	s_waitcnt vmcnt(15)
	v_mul_f32_e32 v80, v80, v112
	ds_write_b32 v22, v80 offset:4224
	s_waitcnt vmcnt(14)
	v_mul_f32_e32 v81, v81, v113
	ds_write_b32 v22, v81 offset:4488
	s_waitcnt vmcnt(13)
	v_mul_f32_e32 v82, v82, v114
	ds_write_b32 v22, v82 offset:4752
	s_waitcnt vmcnt(12)
	v_mul_f32_e32 v83, v83, v115
	ds_write_b32 v22, v83 offset:5016
	s_waitcnt vmcnt(11)
	v_mul_f32_e32 v84, v84, v116
	ds_write_b32 v22, v84 offset:5280
	s_waitcnt vmcnt(10)
	v_mul_f32_e32 v85, v85, v117
	ds_write_b32 v22, v85 offset:5544
	s_waitcnt vmcnt(9)
	v_mul_f32_e32 v86, v86, v118
	ds_write_b32 v22, v86 offset:5808
	s_waitcnt vmcnt(8)
	v_mul_f32_e32 v87, v87, v119
	ds_write_b32 v22, v87 offset:6072
	s_waitcnt vmcnt(7)
	v_mul_f32_e32 v88, v88, v120
	ds_write_b32 v22, v88 offset:6336
	s_waitcnt vmcnt(6)
	v_mul_f32_e32 v89, v89, v121
	ds_write_b32 v22, v89 offset:6600
	s_waitcnt vmcnt(5)
	v_mul_f32_e32 v90, v90, v122
	ds_write_b32 v22, v90 offset:6864
	s_waitcnt vmcnt(4)
	v_mul_f32_e32 v91, v91, v123
	ds_write_b32 v22, v91 offset:7128
	s_waitcnt vmcnt(3)
	v_mul_f32_e32 v92, v92, v124
	ds_write_b32 v22, v92 offset:7392
	s_waitcnt vmcnt(2)
	v_mul_f32_e32 v93, v93, v125
	ds_write_b32 v22, v93 offset:7656
	s_waitcnt vmcnt(1)
	v_mul_f32_e32 v94, v94, v126
	ds_write_b32 v22, v94 offset:7920
	s_waitcnt vmcnt(0)
	v_mul_f32_e32 v95, v95, v127
	ds_write_b32 v22, v95 offset:8184
	s_branch .LBB0_21

.LBB0_953:
	s_lshl_b32 s10, s8, 1
	s_lshl_b32 s11, s1, 1
	v_add_u32_e32 v36, s10, v6
	v_add_u32_e32 v38, s11, v5
	v_ashrrev_i32_e32 v37, 31, v36
	v_ashrrev_i32_e32 v39, 31, v38
	v_mad_i64_i32 v[40:41], s[16:17], v36, s52, v[0:1]
	v_lshl_add_u64 v[36:37], v[36:37], 2, s[50:51]
	v_mad_i64_i32 v[42:43], s[16:17], v38, s52, v[0:1]
	global_load_dword v52, v[40:41], off
	s_nop 0
	global_load_dword v53, v[42:43], off
	v_lshl_add_u64 v[38:39], v[38:39], 2, s[50:51]
	global_load_dword v54, v[36:37], off
	s_nop 0
	global_load_dword v55, v[38:39], off
	v_add_u32_e32 v36, s10, v10
	v_add_u32_e32 v38, s11, v9
	v_ashrrev_i32_e32 v37, 31, v36
	v_ashrrev_i32_e32 v39, 31, v38
	v_mad_i64_i32 v[40:41], s[16:17], v36, s52, v[0:1]
	v_lshl_add_u64 v[36:37], v[36:37], 2, s[50:51]
	v_mad_i64_i32 v[42:43], s[16:17], v38, s52, v[0:1]
	global_load_dword v56, v[40:41], off
	s_nop 0
	global_load_dword v57, v[42:43], off
	v_lshl_add_u64 v[38:39], v[38:39], 2, s[50:51]
	global_load_dword v58, v[36:37], off
	s_nop 0
	global_load_dword v59, v[38:39], off
	v_add_u32_e32 v36, s10, v14
	v_add_u32_e32 v38, s11, v13
	v_ashrrev_i32_e32 v37, 31, v36
	v_ashrrev_i32_e32 v39, 31, v38
	v_mad_i64_i32 v[40:41], s[16:17], v36, s52, v[0:1]
	v_lshl_add_u64 v[36:37], v[36:37], 2, s[50:51]
	v_mad_i64_i32 v[42:43], s[16:17], v38, s52, v[0:1]
	global_load_dword v60, v[40:41], off
	s_nop 0
	global_load_dword v61, v[42:43], off
	v_lshl_add_u64 v[38:39], v[38:39], 2, s[50:51]
	global_load_dword v62, v[36:37], off
	s_nop 0
	global_load_dword v63, v[38:39], off
	v_add_u32_e32 v36, s10, v18
	v_add_u32_e32 v38, s11, v17
	v_ashrrev_i32_e32 v37, 31, v36
	v_ashrrev_i32_e32 v39, 31, v38
	v_mad_i64_i32 v[40:41], s[16:17], v36, s52, v[0:1]
	v_lshl_add_u64 v[36:37], v[36:37], 2, s[50:51]
	v_mad_i64_i32 v[42:43], s[16:17], v38, s52, v[0:1]
	global_load_dword v64, v[40:41], off
	s_nop 0
	global_load_dword v65, v[42:43], off
	v_lshl_add_u64 v[38:39], v[38:39], 2, s[50:51]
	global_load_dword v66, v[36:37], off
	s_nop 0
	global_load_dword v67, v[38:39], off
	v_add_u32_e32 v36, s10, v22
	v_add_u32_e32 v38, s11, v21
	v_ashrrev_i32_e32 v37, 31, v36
	v_ashrrev_i32_e32 v39, 31, v38
	v_mad_i64_i32 v[40:41], s[16:17], v36, s52, v[0:1]
	v_lshl_add_u64 v[36:37], v[36:37], 2, s[50:51]
	v_mad_i64_i32 v[42:43], s[16:17], v38, s52, v[0:1]
	global_load_dword v68, v[40:41], off
	s_nop 0
	global_load_dword v69, v[42:43], off
	v_lshl_add_u64 v[38:39], v[38:39], 2, s[50:51]
	global_load_dword v70, v[36:37], off
	s_nop 0
	global_load_dword v71, v[38:39], off
	v_add_u32_e32 v36, s10, v26
	v_add_u32_e32 v38, s11, v25
	v_ashrrev_i32_e32 v37, 31, v36
	v_ashrrev_i32_e32 v39, 31, v38
	v_mad_i64_i32 v[40:41], s[16:17], v36, s52, v[0:1]
	v_lshl_add_u64 v[36:37], v[36:37], 2, s[50:51]
	v_mad_i64_i32 v[42:43], s[16:17], v38, s52, v[0:1]
	global_load_dword v72, v[40:41], off
	s_nop 0
	global_load_dword v73, v[42:43], off
	v_lshl_add_u64 v[38:39], v[38:39], 2, s[50:51]
	global_load_dword v74, v[36:37], off
	s_nop 0
	global_load_dword v75, v[38:39], off
	v_add_u32_e32 v36, s10, v30
	v_add_u32_e32 v38, s11, v29
	v_ashrrev_i32_e32 v37, 31, v36
	v_ashrrev_i32_e32 v39, 31, v38
	v_mad_i64_i32 v[40:41], s[16:17], v36, s52, v[0:1]
	v_lshl_add_u64 v[36:37], v[36:37], 2, s[50:51]
	v_mad_i64_i32 v[42:43], s[16:17], v38, s52, v[0:1]
	global_load_dword v76, v[40:41], off
	s_nop 0
	global_load_dword v77, v[42:43], off
	v_lshl_add_u64 v[38:39], v[38:39], 2, s[50:51]
	global_load_dword v78, v[36:37], off
	s_nop 0
	global_load_dword v79, v[38:39], off
	v_add_u32_e32 v36, s10, v34
	v_add_u32_e32 v38, s11, v33
	v_ashrrev_i32_e32 v37, 31, v36
	v_ashrrev_i32_e32 v39, 31, v38
	v_mad_i64_i32 v[40:41], s[16:17], v36, s52, v[0:1]
	v_lshl_add_u64 v[36:37], v[36:37], 2, s[50:51]
	v_mad_i64_i32 v[42:43], s[16:17], v38, s52, v[0:1]
	global_load_dword v80, v[40:41], off
	s_nop 0
	global_load_dword v81, v[42:43], off
	v_lshl_add_u64 v[38:39], v[38:39], 2, s[50:51]
	global_load_dword v82, v[36:37], off
	s_nop 0
	global_load_dword v83, v[38:39], off
	s_waitcnt vmcnt(0)
	v_add_u32_e32 v45, s10, v4
	v_add_u32_e32 v44, s11, v3
	v_mad_u64_u32 v[38:39], s[16:17], v45, s53, v[2:3]
	v_add_u32_e32 v45, s10, v8
	s_add_i32 s8, s8, 16
	s_add_i32 s1, s1, 16
	s_add_i32 s9, s9, -16
	s_cmp_lg_u32 s9, 0
	v_pk_mul_f32 v[36:37], v[52:53], v[54:55]
	v_mad_u64_u32 v[40:41], s[16:17], v44, s53, v[2:3]
	ds_write_b32 v38, v36
	ds_write_b32 v40, v37
	v_add_u32_e32 v44, s11, v7
	v_mad_u64_u32 v[38:39], s[16:17], v45, s53, v[2:3]
	v_add_u32_e32 v45, s10, v12
	v_pk_mul_f32 v[36:37], v[56:57], v[58:59]
	v_mad_u64_u32 v[40:41], s[16:17], v44, s53, v[2:3]
	ds_write_b32 v38, v36
	ds_write_b32 v40, v37
	v_add_u32_e32 v44, s11, v11
	v_mad_u64_u32 v[38:39], s[16:17], v45, s53, v[2:3]
	v_add_u32_e32 v45, s10, v16
	v_pk_mul_f32 v[36:37], v[60:61], v[62:63]
	v_mad_u64_u32 v[40:41], s[16:17], v44, s53, v[2:3]
	ds_write_b32 v38, v36
	ds_write_b32 v40, v37
	v_add_u32_e32 v44, s11, v15
	v_mad_u64_u32 v[38:39], s[16:17], v45, s53, v[2:3]
	v_add_u32_e32 v45, s10, v20
	v_pk_mul_f32 v[36:37], v[64:65], v[66:67]
	v_mad_u64_u32 v[40:41], s[16:17], v44, s53, v[2:3]
	ds_write_b32 v38, v36
	ds_write_b32 v40, v37
	v_add_u32_e32 v44, s11, v19
	v_mad_u64_u32 v[38:39], s[16:17], v45, s53, v[2:3]
	v_add_u32_e32 v45, s10, v24
	v_pk_mul_f32 v[36:37], v[68:69], v[70:71]
	v_mad_u64_u32 v[40:41], s[16:17], v44, s53, v[2:3]
	ds_write_b32 v38, v36
	ds_write_b32 v40, v37
	v_add_u32_e32 v44, s11, v23
	v_mad_u64_u32 v[38:39], s[16:17], v45, s53, v[2:3]
	v_add_u32_e32 v45, s10, v28
	v_pk_mul_f32 v[36:37], v[72:73], v[74:75]
	v_mad_u64_u32 v[40:41], s[16:17], v44, s53, v[2:3]
	ds_write_b32 v38, v36
	ds_write_b32 v40, v37
	v_add_u32_e32 v44, s11, v27
	v_mad_u64_u32 v[38:39], s[16:17], v45, s53, v[2:3]
	v_add_u32_e32 v45, s10, v32
	v_pk_mul_f32 v[36:37], v[76:77], v[78:79]
	v_mad_u64_u32 v[40:41], s[16:17], v44, s53, v[2:3]
	ds_write_b32 v38, v36
	ds_write_b32 v40, v37
	v_add_u32_e32 v44, s11, v31
	v_mad_u64_u32 v[38:39], s[16:17], v45, s53, v[2:3]
	v_pk_mul_f32 v[36:37], v[80:81], v[82:83]
	v_mad_u64_u32 v[40:41], s[16:17], v44, s53, v[2:3]
	ds_write_b32 v38, v36
	ds_write_b32 v40, v37
	s_cbranch_scc1 .LBB0_953
	v_lshlrev_b32_e32 v0, 3, v35
	v_ashrrev_i32_e32 v22, 3, v35
	v_and_b32_e32 v0, 56, v0
	v_mul_u32_u24_e32 v1, 0x84, v0
	v_lshlrev_b32_e32 v194, 1, v0
	v_lshlrev_b32_e32 v0, 2, v22
	s_waitcnt lgkmcnt(0)
	v_add3_u32 v26, s70, v1, v0
	s_ashr_i32 s1, s0, 31
	ds_read2_b32 v[6:7], v26 offset0:33 offset1:41
	ds_read2_b32 v[8:9], v26 offset1:8
	ds_read2_b32 v[10:11], v26 offset0:66 offset1:74
	ds_read2_b32 v[12:13], v26 offset0:99 offset1:107
	ds_read2_b32 v[14:15], v26 offset0:132 offset1:140
	ds_read2_b32 v[16:17], v26 offset0:165 offset1:173
	ds_read2_b32 v[18:19], v26 offset0:198 offset1:206
	ds_read2_b32 v[20:21], v26 offset0:231 offset1:239
	s_lshl_b64 s[0:1], s[0:1], 1
	v_readlane_b32 s8, v252, 23
	s_add_u32 s0, s8, s0
	v_readlane_b32 s8, v252, 24
	v_add_u32_e32 v22, s7, v22
	s_addc_u32 s1, s8, s1
	v_ashrrev_i32_e32 v23, 31, v22
	v_lshl_add_u64 v[4:5], s[0:1], 0, v[194:195]
	v_lshlrev_b64 v[24:25], 11, v[22:23]
	s_waitcnt lgkmcnt(6)
	v_cvt_pk_bf16_f32 v0, v8, v6
	s_waitcnt lgkmcnt(4)
	v_cvt_pk_bf16_f32 v1, v10, v12
	s_waitcnt lgkmcnt(2)
	v_cvt_pk_bf16_f32 v2, v14, v16
	s_waitcnt lgkmcnt(0)
	v_cvt_pk_bf16_f32 v3, v18, v20
	v_lshl_add_u64 v[24:25], v[4:5], 0, v[24:25]
	v_add_u32_e32 v6, 8, v22
	global_store_dwordx4 v[24:25], v[0:3], off
	v_add_u32_e32 v24, 16, v22
	v_ashrrev_i32_e32 v25, 31, v24
	v_cvt_pk_bf16_f32 v0, v9, v7
	v_ashrrev_i32_e32 v7, 31, v6
	v_lshlrev_b64 v[6:7], 11, v[6:7]
	v_cvt_pk_bf16_f32 v1, v11, v13
	v_cvt_pk_bf16_f32 v2, v15, v17
	v_cvt_pk_bf16_f32 v3, v19, v21
	v_lshl_add_u64 v[6:7], v[4:5], 0, v[6:7]
	global_store_dwordx4 v[6:7], v[0:3], off
	ds_read2_b32 v[6:7], v26 offset0:49 offset1:57
	ds_read2_b32 v[8:9], v26 offset0:16 offset1:24
	ds_read2_b32 v[10:11], v26 offset0:82 offset1:90
	ds_read2_b32 v[12:13], v26 offset0:115 offset1:123
	ds_read2_b32 v[14:15], v26 offset0:148 offset1:156
	ds_read2_b32 v[16:17], v26 offset0:181 offset1:189
	ds_read2_b32 v[18:19], v26 offset0:214 offset1:222
	ds_read2_b32 v[20:21], v26 offset0:247 offset1:255
	v_lshlrev_b64 v[24:25], 11, v[24:25]
	s_waitcnt lgkmcnt(6)
	v_cvt_pk_bf16_f32 v0, v8, v6
	s_waitcnt lgkmcnt(4)
	v_cvt_pk_bf16_f32 v1, v10, v12
	s_waitcnt lgkmcnt(2)
	v_cvt_pk_bf16_f32 v2, v14, v16
	s_waitcnt lgkmcnt(0)
	v_cvt_pk_bf16_f32 v3, v18, v20
	v_lshl_add_u64 v[24:25], v[4:5], 0, v[24:25]
	v_add_u32_e32 v6, 24, v22
	global_store_dwordx4 v[24:25], v[0:3], off
	s_add_i32 s3, s3, s89
	s_cmpk_lt_i32 s3, 0xd00
	v_cvt_pk_bf16_f32 v0, v9, v7
	v_ashrrev_i32_e32 v7, 31, v6
	v_lshlrev_b64 v[6:7], 11, v[6:7]
	v_cvt_pk_bf16_f32 v1, v11, v13
	v_cvt_pk_bf16_f32 v2, v15, v17
	v_cvt_pk_bf16_f32 v3, v19, v21
	v_lshl_add_u64 v[4:5], v[4:5], 0, v[6:7]
	global_store_dwordx4 v[4:5], v[0:3], off
	s_waitcnt lgkmcnt(0)
	s_cbranch_scc1 .LBB0_923
